# prep item QK-norm/rotary: 88 ds_bpermute lane exchanges replaced by DPP moves (quad_perm / row_half_mirror)
# speedup vs baseline: 1.0054x; 1.0054x over previous
;     __device__ __forceinline__ const float* in(int i) const { return (const float*)(const __attribute__((address_space(1))) float*)ld(i); }
; __device__ __forceinline__ float lo16(unsigned w) { return __uint_as_float(w << 16); }
; __device__ __forceinline__ float hi16(unsigned w) { return __uint_as_float(w & 0xffff0000u); }
; __device__ __forceinline__ void prep_pool_item(const KPD& kp, int l, int sc, unsigned char* lds, int tid, int lane, int wave) {
;     ...
;       bf16* prow_ = P + (size_t)(rowbase + t) * INP + 8 * sub;
;       v4u vin[8];
; #pragma unroll
;       for (int hd = 0; hd < 8; ++hd) vin[hd] = *(const v4u*)(prow_ + (hd < 6 ? C_AQ + hd * 64 : C_AK + (hd - 6) * 64));
;       const f32x4 gq0 = *(const f32x4*)(kp.in(I_QNG) + l * 64 + 8 * sub), gq1 = *(const f32x4*)(kp.in(I_QNG) + l * 64 + 8 * sub + 4);
;       const f32x4 gk0 = *(const f32x4*)(kp.in(I_KNG) + l * 64 + 8 * sub), gk1 = *(const f32x4*)(kp.in(I_KNG) + l * 64 + 8 * sub + 4);
; #pragma unroll
;       for (int hd = 0; hd < 8; ++hd) {
;           const f32x4 g0 = hd < 6 ? gq0 : gk0, g1 = hd < 6 ? gq1 : gk1;
;           const float osc = hd < 6 ? 0.18033688011112042f : 1.0f;
;           const v4u v = vin[hd];
;           float x[8] = {lo16(v.x), hi16(v.x), lo16(v.y), hi16(v.y), lo16(v.z), hi16(v.z), lo16(v.w), hi16(v.w)};
;           float ss = 0.f;
; #pragma unroll
;           for (int i = 0; i < 8; ++i) ss += x[i] * x[i];
;           ss += __shfl_xor(ss, 1); ss += __shfl_xor(ss, 2); ss += __shfl_xor(ss, 4);
;           const float rstd = 1.0f / sqrtf(ss * (1.f / 64.f) + EPS);
;           x[0] *= rstd * g0.x; x[1] *= rstd * g0.y; x[2] *= rstd * g0.z; x[3] *= rstd * g0.w; x[4] *= rstd * g1.x; x[5] *= rstd * g1.y; x[6] *= rstd * g1.z; x[7] *= rstd * g1.w;
;           if (!isctx) {
; #pragma unroll
;               for (int i = 0; i < 8; ++i) { const float other = __shfl_xor(x[i], 2); x[i] = x[i] * cn[i] + other * sn[i]; } }
.LBB0_279:
	s_and_b64 s[34:35], s[12:13], exec
	s_mov_b32 s31, 0xff00
	s_cselect_b32 s31, 0x6000, s31
	s_cselect_b32 s11, s11, s17
	s_lshl_b32 s10, s10, 6
	s_and_b32 s17, s31, s10
	s_lshl_b32 s10, s11, 6
	s_add_i32 s17, s17, s10
	v_add_u32_e32 v4, s17, v126
	v_mov_b64_e32 v[2:3], s[2:3]
	v_mad_i64_i32 v[2:3], s[10:11], v4, s33, v[2:3]
	s_mov_b64 s[10:11], 0x7800000
	s_nop 0
	v_lshl_add_u64 v[94:95], v[2:3], 0, s[10:11]
	v_lshlrev_b32_e32 v34, 1, v36
	v_lshl_add_u64 v[106:107], v[94:95], 0, v[34:35]
	global_load_dwordx4 v[112:115], v[106:107], off offset:2368
	global_load_dwordx4 v[66:69], v[106:107], off offset:2496
	global_load_dwordx4 v[62:65], v[106:107], off offset:2624
	global_load_dwordx4 v[58:61], v[106:107], off offset:2752
	global_load_dwordx4 v[54:57], v[106:107], off offset:2880
	global_load_dwordx4 v[50:53], v[106:107], off offset:3008
	global_load_dwordx4 v[14:17], v[106:107], off offset:3136
	global_load_dwordx4 v[10:13], v[106:107], off offset:3264
	v_mov_b32_e32 v4, 0x26458
	ds_read_b64 v[2:3], v4
	v_lshlrev_b32_e32 v8, 2, v36
	v_mov_b32_e32 v6, 0x26460
	v_and_b32_e32 v34, 64, v216
	v_xor_b32_e32 v9, 1, v216
	s_waitcnt lgkmcnt(0)
	v_readfirstlane_b32 s10, v2
	v_readfirstlane_b32 s11, v3
	s_add_u32 s10, s10, s22
	s_addc_u32 s11, s11, s23
	v_add_u32_e32 v38, 64, v34
	v_cmp_lt_i32_e32 vcc, v9, v38
	v_xor_b32_e32 v41, 4, v216
	global_load_dwordx4 v[42:45], v8, s[10:11]
	ds_read_b64 v[2:3], v4
	v_cndmask_b32_e32 v9, v216, v9, vcc
	v_lshlrev_b32_e32 v83, 2, v9
	s_waitcnt lgkmcnt(0)
	v_readfirstlane_b32 s10, v2
	v_readfirstlane_b32 s11, v3
	s_add_u32 s10, s10, s22
	s_addc_u32 s11, s11, s23
	s_waitcnt vmcnt(8)
	v_lshlrev_b32_e32 v116, 16, v112
	s_nop 0
	global_load_dwordx4 v[46:49], v8, s[10:11] offset:16
	ds_read_b64 v[2:3], v6
	v_and_b32_e32 v117, 0xffff0000, v112
	v_lshlrev_b32_e32 v112, 16, v113
	v_and_b32_e32 v113, 0xffff0000, v113
	v_pk_mul_f32 v[152:153], v[116:117], v[116:117]
	s_waitcnt lgkmcnt(0)
	v_readfirstlane_b32 s10, v2
	v_readfirstlane_b32 s11, v3
	s_add_u32 s10, s10, s22
	s_addc_u32 s11, s11, s23
	v_pk_mul_f32 v[154:155], v[112:113], v[112:113]
	v_add_f32_e32 v34, v152, v153
	v_lshlrev_b32_e32 v150, 16, v114
	global_load_dwordx4 v[2:5], v8, s[10:11]
	ds_read_b64 v[6:7], v6
	v_and_b32_e32 v151, 0xffff0000, v114
	v_add_f32_e32 v34, v154, v34
	v_pk_mul_f32 v[156:157], v[150:151], v[150:151]
	v_add_f32_e32 v34, v155, v34
	s_waitcnt lgkmcnt(0)
	v_readfirstlane_b32 s10, v6
	v_readfirstlane_b32 s11, v7
	s_add_u32 s10, s10, s22
	s_addc_u32 s11, s11, s23
	v_and_b32_e32 v118, 0xffff0000, v115
	v_lshlrev_b32_e32 v119, 16, v115
	v_add_f32_e32 v34, v156, v34
	global_load_dwordx4 v[6:9], v8, s[10:11] offset:16
	v_pk_mul_f32 v[114:115], v[118:119], v[118:119]
	v_add_f32_e32 v34, v157, v34
	v_add_f32_e32 v34, v115, v34
	v_add_f32_e32 v39, v114, v34
	s_nop 1
	v_mov_b32_dpp v40, v39 quad_perm:[1,0,3,2] row_mask:0xf bank_mask:0xf
	v_xor_b32_e32 v34, 2, v216
	v_cmp_lt_i32_e32 vcc, v34, v38
	s_waitcnt lgkmcnt(0)
	v_add_f32_e32 v39, v39, v40
	v_cndmask_b32_e32 v34, v216, v34, vcc
	v_lshlrev_b32_e32 v34, 2, v34
	v_mov_b32_dpp v40, v39 quad_perm:[2,3,0,1] row_mask:0xf bank_mask:0xf
	v_cmp_lt_i32_e32 vcc, v41, v38
	s_nop 1
	v_cndmask_b32_e32 v38, v216, v41, vcc
	v_lshlrev_b32_e32 v85, 2, v38
	s_waitcnt lgkmcnt(0)
	v_add_f32_e32 v38, v39, v40
	s_nop 1
	v_mov_b32_dpp v39, v38 row_half_mirror row_mask:0xf bank_mask:0xf
	v_cndmask_b32_e64 v40, 0, 1, s[12:13]
	s_waitcnt lgkmcnt(0)
	v_add_f32_e32 v38, v38, v39
	v_fmamk_f32 v38, v38, 0x3c800000, v205
	v_mul_f32_e32 v39, 0x4f800000, v38
	v_cmp_gt_f32_e32 vcc, s88, v38
	s_nop 1
	v_cndmask_b32_e32 v38, v38, v39, vcc
	v_sqrt_f32_e32 v39, v38
	s_nop 0
	v_add_u32_e32 v41, -1, v39
	v_add_u32_e32 v87, 1, v39
	v_fma_f32 v89, -v41, v39, v38
	v_fma_f32 v91, -v87, v39, v38
	v_cmp_ge_f32_e64 s[10:11], 0, v89
	s_nop 1
	v_cndmask_b32_e64 v39, v39, v41, s[10:11]
	v_cmp_lt_f32_e64 s[10:11], 0, v91
	s_nop 1
	v_cndmask_b32_e64 v39, v39, v87, s[10:11]
	v_mul_f32_e32 v41, 0x37800000, v39
	v_cndmask_b32_e32 v39, v39, v41, vcc
	v_cmp_class_f32_e32 vcc, v38, v206
	s_nop 1
	v_cndmask_b32_e32 v38, v39, v38, vcc
	v_div_scale_f32 v39, s[10:11], v38, v38, 1.0
	v_rcp_f32_e32 v41, v39
	v_cmp_ne_u32_e64 s[10:11], 1, v40
	v_div_scale_f32 v40, vcc, 1.0, v38, 1.0
	v_fma_f32 v87, -v39, v41, 1.0
	v_fmac_f32_e32 v41, v87, v41
	v_mul_f32_e32 v87, v40, v41
	v_fma_f32 v89, -v39, v87, v40
	v_fmac_f32_e32 v87, v89, v41
	v_fma_f32 v39, -v39, v87, v40
	v_div_fmas_f32 v39, v39, v41, v87
	v_div_fixup_f32 v114, v39, v38, 1.0
	s_waitcnt vmcnt(3)
	v_pk_mul_f32 v[152:153], v[42:43], v[114:115] op_sel_hi:[1,0]
	v_pk_mul_f32 v[154:155], v[44:45], v[114:115] op_sel_hi:[1,0]
	s_waitcnt vmcnt(2)
	v_pk_mul_f32 v[156:157], v[46:47], v[114:115] op_sel_hi:[1,0]
	v_pk_mul_f32 v[158:159], v[48:49], v[114:115] op_sel_hi:[1,0]
	s_andn2_b64 vcc, exec, s[12:13]
	v_pk_mul_f32 v[116:117], v[152:153], v[116:117]
	v_pk_mul_f32 v[114:115], v[154:155], v[112:113]
	v_pk_mul_f32 v[112:113], v[156:157], v[150:151]
	v_pk_mul_f32 v[118:119], v[158:159], v[118:119] op_sel:[0,1] op_sel_hi:[1,0]
	s_cbranch_vccnz .LBB0_281
	s_nop 0
	v_mov_b32_dpp v157, v119 quad_perm:[2,3,0,1] row_mask:0xf bank_mask:0xf
	v_mov_b32_dpp v150, v116 quad_perm:[2,3,0,1] row_mask:0xf bank_mask:0xf
	v_mov_b32_dpp v151, v117 quad_perm:[2,3,0,1] row_mask:0xf bank_mask:0xf
	v_mov_b32_dpp v152, v114 quad_perm:[2,3,0,1] row_mask:0xf bank_mask:0xf
	v_mov_b32_dpp v153, v115 quad_perm:[2,3,0,1] row_mask:0xf bank_mask:0xf
	v_mov_b32_dpp v154, v112 quad_perm:[2,3,0,1] row_mask:0xf bank_mask:0xf
	v_mov_b32_dpp v155, v113 quad_perm:[2,3,0,1] row_mask:0xf bank_mask:0xf
	v_mov_b32_dpp v38, v118 quad_perm:[2,3,0,1] row_mask:0xf bank_mask:0xf
	v_mov_b32_e32 v156, v119
	s_waitcnt lgkmcnt(0)
	v_pk_mul_f32 v[156:157], v[102:103], v[156:157]
	s_waitcnt lgkmcnt(0)
	v_pk_mul_f32 v[150:151], v[104:105], v[150:151]
	s_waitcnt lgkmcnt(0)
	v_pk_mul_f32 v[152:153], v[108:109], v[152:153]
	s_waitcnt lgkmcnt(0)
	v_pk_mul_f32 v[154:155], v[110:111], v[154:155]
	v_mul_f32_e32 v118, v79, v118
	s_waitcnt lgkmcnt(0)
	v_mul_f32_e32 v158, v81, v38
	v_mov_b32_e32 v119, v156
	v_mov_b32_e32 v159, v157
	v_pk_fma_f32 v[116:117], v[96:97], v[116:117], v[150:151]
	v_pk_fma_f32 v[114:115], v[98:99], v[114:115], v[152:153]
	v_pk_fma_f32 v[112:113], v[100:101], v[112:113], v[154:155]
	v_pk_add_f32 v[118:119], v[118:119], v[158:159]
; __device__ __forceinline__ unsigned pk2(float lo, float hi) { return cvtpk(lo, hi); }
; __device__ __forceinline__ float lo16(unsigned w) { return __uint_as_float(w << 16); }
; __device__ __forceinline__ float hi16(unsigned w) { return __uint_as_float(w & 0xffff0000u); }
; __device__ __forceinline__ void prep_pool_item(const KPD& kp, int l, int sc, unsigned char* lds, int tid, int lane, int wave) {
;     ...
;           const v4u v = vin[hd];
;           float x[8] = {lo16(v.x), hi16(v.x), lo16(v.y), hi16(v.y), lo16(v.z), hi16(v.z), lo16(v.w), hi16(v.w)};
;           float ss = 0.f;
; #pragma unroll
;           for (int i = 0; i < 8; ++i) ss += x[i] * x[i];
;           ss += __shfl_xor(ss, 1); ss += __shfl_xor(ss, 2); ss += __shfl_xor(ss, 4);
;           const float rstd = 1.0f / sqrtf(ss * (1.f / 64.f) + EPS);
;           x[0] *= rstd * g0.x; x[1] *= rstd * g0.y; x[2] *= rstd * g0.z; x[3] *= rstd * g0.w; x[4] *= rstd * g1.x; x[5] *= rstd * g1.y; x[6] *= rstd * g1.z; x[7] *= rstd * g1.w;
;           if (!isctx) {
; #pragma unroll
;               for (int i = 0; i < 8; ++i) { const float other = __shfl_xor(x[i], 2); x[i] = x[i] * cn[i] + other * sn[i]; } }
;           v4u o; o.x = pk2(x[0] * osc, x[1] * osc); o.y = pk2(x[2] * osc, x[3] * osc); o.z = pk2(x[4] * osc, x[5] * osc); o.w = pk2(x[6] * osc, x[7] * osc);
;           *(v4u*)(prow_ + (hd < 6 ? C_AQ + hd * 64 : C_AK + (hd - 6) * 64)) = o; } }
.LBB0_281:
	v_mul_f32_e32 v38, 0x3e38aa3b, v116
	v_mul_f32_e32 v39, 0x3e38aa3b, v117
	v_cvt_pk_bf16_f32 v150, v38, v39
	v_mul_f32_e32 v38, 0x3e38aa3b, v114
	v_mul_f32_e32 v39, 0x3e38aa3b, v115
	v_cvt_pk_bf16_f32 v151, v38, v39
	v_mul_f32_e32 v38, 0x3e38aa3b, v112
	v_mul_f32_e32 v39, 0x3e38aa3b, v113
	v_lshlrev_b32_e32 v116, 16, v66
	v_and_b32_e32 v117, 0xffff0000, v66
	v_cvt_pk_bf16_f32 v152, v38, v39
	v_mul_f32_e32 v38, 0x3e38aa3b, v118
	v_mul_f32_e32 v39, 0x3e38aa3b, v119
	v_pk_mul_f32 v[118:119], v[116:117], v[116:117]
	v_lshlrev_b32_e32 v66, 16, v67
	v_and_b32_e32 v67, 0xffff0000, v67
	v_cvt_pk_bf16_f32 v153, v38, v39
	global_store_dwordx4 v[106:107], v[150:153], off offset:2368
	v_add_f32_e32 v38, v118, v119
	v_and_b32_e32 v114, 0xffff0000, v69
	v_pk_mul_f32 v[150:151], v[66:67], v[66:67]
	v_lshlrev_b32_e32 v152, 16, v68
	v_and_b32_e32 v153, 0xffff0000, v68
	v_add_f32_e32 v38, v150, v38
	v_lshlrev_b32_e32 v115, 16, v69
	v_pk_mul_f32 v[68:69], v[152:153], v[152:153]
	v_add_f32_e32 v38, v151, v38
	v_add_f32_e32 v38, v68, v38
	v_pk_mul_f32 v[112:113], v[114:115], v[114:115]
	v_add_f32_e32 v38, v69, v38
	v_add_f32_e32 v38, v113, v38
	v_add_f32_e32 v38, v112, v38
	s_nop 1
	v_mov_b32_dpp v39, v38 quad_perm:[1,0,3,2] row_mask:0xf bank_mask:0xf
	s_waitcnt lgkmcnt(0)
	v_add_f32_e32 v38, v38, v39
	s_nop 1
	v_mov_b32_dpp v39, v38 quad_perm:[2,3,0,1] row_mask:0xf bank_mask:0xf
	s_waitcnt lgkmcnt(0)
	v_add_f32_e32 v38, v38, v39
	s_nop 1
	v_mov_b32_dpp v39, v38 row_half_mirror row_mask:0xf bank_mask:0xf
	s_waitcnt lgkmcnt(0)
	v_add_f32_e32 v38, v38, v39
	v_fmamk_f32 v38, v38, 0x3c800000, v205
	v_cmp_gt_f32_e32 vcc, s88, v38
	v_mul_f32_e32 v39, 0x4f800000, v38
	s_nop 0
	v_cndmask_b32_e32 v38, v38, v39, vcc
	v_sqrt_f32_e32 v39, v38
	s_nop 0
	v_add_u32_e32 v40, -1, v39
	v_fma_f32 v41, -v40, v39, v38
	v_cmp_ge_f32_e64 s[12:13], 0, v41
	v_add_u32_e32 v41, 1, v39
	s_nop 0
	v_cndmask_b32_e64 v40, v39, v40, s[12:13]
	v_fma_f32 v39, -v41, v39, v38
	v_cmp_lt_f32_e64 s[12:13], 0, v39
	s_nop 1
	v_cndmask_b32_e64 v39, v40, v41, s[12:13]
	v_mul_f32_e32 v40, 0x37800000, v39
	v_cndmask_b32_e32 v39, v39, v40, vcc
	v_cmp_class_f32_e32 vcc, v38, v206
	s_nop 1
	v_cndmask_b32_e32 v38, v39, v38, vcc
	v_div_scale_f32 v39, s[12:13], v38, v38, 1.0
	v_rcp_f32_e32 v40, v39
	s_nop 0
	v_fma_f32 v41, -v39, v40, 1.0
	v_fmac_f32_e32 v40, v41, v40
	v_div_scale_f32 v41, vcc, 1.0, v38, 1.0
	v_mul_f32_e32 v68, v41, v40
	v_fma_f32 v69, -v39, v68, v41
	v_fmac_f32_e32 v68, v69, v40
	v_fma_f32 v39, -v39, v68, v41
	v_div_fmas_f32 v39, v39, v40, v68
	v_div_fixup_f32 v118, v39, v38, 1.0
	v_pk_mul_f32 v[68:69], v[42:43], v[118:119] op_sel_hi:[1,0]
	s_and_b64 vcc, exec, s[10:11]
	v_pk_mul_f32 v[112:113], v[68:69], v[116:117]
	v_pk_mul_f32 v[68:69], v[44:45], v[118:119] op_sel_hi:[1,0]
	v_pk_mul_f32 v[116:117], v[48:49], v[118:119] op_sel_hi:[1,0]
	v_pk_mul_f32 v[68:69], v[68:69], v[66:67]
	v_pk_mul_f32 v[66:67], v[46:47], v[118:119] op_sel_hi:[1,0]
	v_pk_mul_f32 v[114:115], v[116:117], v[114:115] op_sel:[0,1] op_sel_hi:[1,0]
	v_pk_mul_f32 v[66:67], v[66:67], v[152:153]
	s_cbranch_vccnz .LBB0_283
	v_mov_b32_dpp v153, v115 quad_perm:[2,3,0,1] row_mask:0xf bank_mask:0xf
	v_mov_b32_dpp v116, v112 quad_perm:[2,3,0,1] row_mask:0xf bank_mask:0xf
	v_mov_b32_dpp v117, v113 quad_perm:[2,3,0,1] row_mask:0xf bank_mask:0xf
	v_mov_b32_dpp v118, v68 quad_perm:[2,3,0,1] row_mask:0xf bank_mask:0xf
	v_mov_b32_dpp v119, v69 quad_perm:[2,3,0,1] row_mask:0xf bank_mask:0xf
	v_mov_b32_dpp v150, v66 quad_perm:[2,3,0,1] row_mask:0xf bank_mask:0xf
	v_mov_b32_dpp v151, v67 quad_perm:[2,3,0,1] row_mask:0xf bank_mask:0xf
	v_mov_b32_dpp v38, v114 quad_perm:[2,3,0,1] row_mask:0xf bank_mask:0xf
	v_mov_b32_e32 v152, v115
	s_waitcnt lgkmcnt(0)
	v_pk_mul_f32 v[152:153], v[102:103], v[152:153]
	s_waitcnt lgkmcnt(0)
	v_pk_mul_f32 v[116:117], v[104:105], v[116:117]
	s_waitcnt lgkmcnt(0)
	v_pk_mul_f32 v[118:119], v[108:109], v[118:119]
	s_waitcnt lgkmcnt(0)
	v_pk_mul_f32 v[150:151], v[110:111], v[150:151]
	v_mul_f32_e32 v114, v79, v114
	s_waitcnt lgkmcnt(0)
	v_mul_f32_e32 v154, v81, v38
	v_mov_b32_e32 v115, v152
	v_mov_b32_e32 v155, v153
	v_pk_fma_f32 v[112:113], v[96:97], v[112:113], v[116:117]
	v_pk_fma_f32 v[68:69], v[98:99], v[68:69], v[118:119]
	v_pk_fma_f32 v[66:67], v[100:101], v[66:67], v[150:151]
	v_pk_add_f32 v[114:115], v[114:115], v[154:155]
; __device__ __forceinline__ unsigned pk2(float lo, float hi) { return cvtpk(lo, hi); }
; __device__ __forceinline__ float lo16(unsigned w) { return __uint_as_float(w << 16); }
; __device__ __forceinline__ float hi16(unsigned w) { return __uint_as_float(w & 0xffff0000u); }
; __device__ __forceinline__ void prep_pool_item(const KPD& kp, int l, int sc, unsigned char* lds, int tid, int lane, int wave) {
;     ...
;           const v4u v = vin[hd];
;           float x[8] = {lo16(v.x), hi16(v.x), lo16(v.y), hi16(v.y), lo16(v.z), hi16(v.z), lo16(v.w), hi16(v.w)};
;           float ss = 0.f;
; #pragma unroll
;           for (int i = 0; i < 8; ++i) ss += x[i] * x[i];
;           ss += __shfl_xor(ss, 1); ss += __shfl_xor(ss, 2); ss += __shfl_xor(ss, 4);
;           const float rstd = 1.0f / sqrtf(ss * (1.f / 64.f) + EPS);
;           x[0] *= rstd * g0.x; x[1] *= rstd * g0.y; x[2] *= rstd * g0.z; x[3] *= rstd * g0.w; x[4] *= rstd * g1.x; x[5] *= rstd * g1.y; x[6] *= rstd * g1.z; x[7] *= rstd * g1.w;
;           if (!isctx) {
; #pragma unroll
;               for (int i = 0; i < 8; ++i) { const float other = __shfl_xor(x[i], 2); x[i] = x[i] * cn[i] + other * sn[i]; } }
;           v4u o; o.x = pk2(x[0] * osc, x[1] * osc); o.y = pk2(x[2] * osc, x[3] * osc); o.z = pk2(x[4] * osc, x[5] * osc); o.w = pk2(x[6] * osc, x[7] * osc);
;           *(v4u*)(prow_ + (hd < 6 ? C_AQ + hd * 64 : C_AK + (hd - 6) * 64)) = o; } }
.LBB0_283:
	v_mul_f32_e32 v38, 0x3e38aa3b, v112
	v_mul_f32_e32 v39, 0x3e38aa3b, v113
	v_cvt_pk_bf16_f32 v116, v38, v39
	v_mul_f32_e32 v38, 0x3e38aa3b, v68
	v_mul_f32_e32 v39, 0x3e38aa3b, v69
	v_cvt_pk_bf16_f32 v117, v38, v39
	v_mul_f32_e32 v38, 0x3e38aa3b, v66
	v_mul_f32_e32 v39, 0x3e38aa3b, v67
	v_lshlrev_b32_e32 v112, 16, v62
	v_and_b32_e32 v113, 0xffff0000, v62
	v_cvt_pk_bf16_f32 v118, v38, v39
	v_mul_f32_e32 v38, 0x3e38aa3b, v114
	v_mul_f32_e32 v39, 0x3e38aa3b, v115
	v_pk_mul_f32 v[114:115], v[112:113], v[112:113]
	v_lshlrev_b32_e32 v62, 16, v63
	v_and_b32_e32 v63, 0xffff0000, v63
	v_cvt_pk_bf16_f32 v119, v38, v39
	global_store_dwordx4 v[106:107], v[116:119], off offset:2496
	v_add_f32_e32 v38, v114, v115
	v_and_b32_e32 v68, 0xffff0000, v65
	v_pk_mul_f32 v[116:117], v[62:63], v[62:63]
	v_lshlrev_b32_e32 v118, 16, v64
	v_and_b32_e32 v119, 0xffff0000, v64
	v_add_f32_e32 v38, v116, v38
	v_lshlrev_b32_e32 v69, 16, v65
	v_pk_mul_f32 v[64:65], v[118:119], v[118:119]
	v_add_f32_e32 v38, v117, v38
	v_add_f32_e32 v38, v64, v38
	v_pk_mul_f32 v[66:67], v[68:69], v[68:69]
	v_add_f32_e32 v38, v65, v38
	v_add_f32_e32 v38, v67, v38
	v_add_f32_e32 v38, v66, v38
	s_nop 1
	v_mov_b32_dpp v39, v38 quad_perm:[1,0,3,2] row_mask:0xf bank_mask:0xf
	s_waitcnt lgkmcnt(0)
	v_add_f32_e32 v38, v38, v39
	s_nop 1
	v_mov_b32_dpp v39, v38 quad_perm:[2,3,0,1] row_mask:0xf bank_mask:0xf
	s_waitcnt lgkmcnt(0)
	v_add_f32_e32 v38, v38, v39
	s_nop 1
	v_mov_b32_dpp v39, v38 row_half_mirror row_mask:0xf bank_mask:0xf
	s_waitcnt lgkmcnt(0)
	v_add_f32_e32 v38, v38, v39
	v_fmamk_f32 v38, v38, 0x3c800000, v205
	v_cmp_gt_f32_e32 vcc, s88, v38
	v_mul_f32_e32 v39, 0x4f800000, v38
	s_nop 0
	v_cndmask_b32_e32 v38, v38, v39, vcc
	v_sqrt_f32_e32 v39, v38
	s_nop 0
	v_add_u32_e32 v40, -1, v39
	v_fma_f32 v41, -v40, v39, v38
	v_cmp_ge_f32_e64 s[12:13], 0, v41
	v_add_u32_e32 v41, 1, v39
	s_nop 0
	v_cndmask_b32_e64 v40, v39, v40, s[12:13]
	v_fma_f32 v39, -v41, v39, v38
	v_cmp_lt_f32_e64 s[12:13], 0, v39
	s_nop 1
	v_cndmask_b32_e64 v39, v40, v41, s[12:13]
	v_mul_f32_e32 v40, 0x37800000, v39
	v_cndmask_b32_e32 v39, v39, v40, vcc
	v_cmp_class_f32_e32 vcc, v38, v206
	s_nop 1
	v_cndmask_b32_e32 v38, v39, v38, vcc
	v_div_scale_f32 v39, s[12:13], v38, v38, 1.0
	v_rcp_f32_e32 v40, v39
	s_nop 0
	v_fma_f32 v41, -v39, v40, 1.0
	v_fmac_f32_e32 v40, v41, v40
	v_div_scale_f32 v41, vcc, 1.0, v38, 1.0
	v_mul_f32_e32 v64, v41, v40
	v_fma_f32 v65, -v39, v64, v41
	v_fmac_f32_e32 v64, v65, v40
	v_fma_f32 v39, -v39, v64, v41
	v_div_fmas_f32 v39, v39, v40, v64
	v_div_fixup_f32 v114, v39, v38, 1.0
	v_pk_mul_f32 v[64:65], v[42:43], v[114:115] op_sel_hi:[1,0]
	s_and_b64 vcc, exec, s[10:11]
	v_pk_mul_f32 v[66:67], v[64:65], v[112:113]
	v_pk_mul_f32 v[64:65], v[44:45], v[114:115] op_sel_hi:[1,0]
	v_pk_mul_f32 v[112:113], v[48:49], v[114:115] op_sel_hi:[1,0]
	v_pk_mul_f32 v[64:65], v[64:65], v[62:63]
	v_pk_mul_f32 v[62:63], v[46:47], v[114:115] op_sel_hi:[1,0]
	v_pk_mul_f32 v[68:69], v[112:113], v[68:69] op_sel:[0,1] op_sel_hi:[1,0]
	v_pk_mul_f32 v[62:63], v[62:63], v[118:119]
	s_cbranch_vccnz .LBB0_285
	v_mov_b32_dpp v119, v69 quad_perm:[2,3,0,1] row_mask:0xf bank_mask:0xf
	v_mov_b32_dpp v112, v66 quad_perm:[2,3,0,1] row_mask:0xf bank_mask:0xf
	v_mov_b32_dpp v113, v67 quad_perm:[2,3,0,1] row_mask:0xf bank_mask:0xf
	v_mov_b32_dpp v114, v64 quad_perm:[2,3,0,1] row_mask:0xf bank_mask:0xf
	v_mov_b32_dpp v115, v65 quad_perm:[2,3,0,1] row_mask:0xf bank_mask:0xf
	v_mov_b32_dpp v116, v62 quad_perm:[2,3,0,1] row_mask:0xf bank_mask:0xf
	v_mov_b32_dpp v117, v63 quad_perm:[2,3,0,1] row_mask:0xf bank_mask:0xf
	v_mov_b32_dpp v38, v68 quad_perm:[2,3,0,1] row_mask:0xf bank_mask:0xf
	v_mov_b32_e32 v118, v69
	s_waitcnt lgkmcnt(0)
	v_pk_mul_f32 v[118:119], v[102:103], v[118:119]
	s_waitcnt lgkmcnt(0)
	v_pk_mul_f32 v[112:113], v[104:105], v[112:113]
	s_waitcnt lgkmcnt(0)
	v_pk_mul_f32 v[114:115], v[108:109], v[114:115]
	s_waitcnt lgkmcnt(0)
	v_pk_mul_f32 v[116:117], v[110:111], v[116:117]
	v_mul_f32_e32 v68, v79, v68
	s_waitcnt lgkmcnt(0)
	v_mul_f32_e32 v150, v81, v38
	v_mov_b32_e32 v69, v118
	v_mov_b32_e32 v151, v119
	v_pk_fma_f32 v[66:67], v[96:97], v[66:67], v[112:113]
	v_pk_fma_f32 v[64:65], v[98:99], v[64:65], v[114:115]
	v_pk_fma_f32 v[62:63], v[100:101], v[62:63], v[116:117]
	v_pk_add_f32 v[68:69], v[68:69], v[150:151]
; __device__ __forceinline__ unsigned pk2(float lo, float hi) { return cvtpk(lo, hi); }
; __device__ __forceinline__ float lo16(unsigned w) { return __uint_as_float(w << 16); }
; __device__ __forceinline__ float hi16(unsigned w) { return __uint_as_float(w & 0xffff0000u); }
; __device__ __forceinline__ void prep_pool_item(const KPD& kp, int l, int sc, unsigned char* lds, int tid, int lane, int wave) {
;     ...
;           const v4u v = vin[hd];
;           float x[8] = {lo16(v.x), hi16(v.x), lo16(v.y), hi16(v.y), lo16(v.z), hi16(v.z), lo16(v.w), hi16(v.w)};
;           float ss = 0.f;
; #pragma unroll
;           for (int i = 0; i < 8; ++i) ss += x[i] * x[i];
;           ss += __shfl_xor(ss, 1); ss += __shfl_xor(ss, 2); ss += __shfl_xor(ss, 4);
;           const float rstd = 1.0f / sqrtf(ss * (1.f / 64.f) + EPS);
;           x[0] *= rstd * g0.x; x[1] *= rstd * g0.y; x[2] *= rstd * g0.z; x[3] *= rstd * g0.w; x[4] *= rstd * g1.x; x[5] *= rstd * g1.y; x[6] *= rstd * g1.z; x[7] *= rstd * g1.w;
;           if (!isctx) {
; #pragma unroll
;               for (int i = 0; i < 8; ++i) { const float other = __shfl_xor(x[i], 2); x[i] = x[i] * cn[i] + other * sn[i]; } }
;           v4u o; o.x = pk2(x[0] * osc, x[1] * osc); o.y = pk2(x[2] * osc, x[3] * osc); o.z = pk2(x[4] * osc, x[5] * osc); o.w = pk2(x[6] * osc, x[7] * osc);
;           *(v4u*)(prow_ + (hd < 6 ? C_AQ + hd * 64 : C_AK + (hd - 6) * 64)) = o; } }
.LBB0_285:
	v_mul_f32_e32 v38, 0x3e38aa3b, v66
	v_mul_f32_e32 v39, 0x3e38aa3b, v67
	v_cvt_pk_bf16_f32 v112, v38, v39
	v_mul_f32_e32 v38, 0x3e38aa3b, v64
	v_mul_f32_e32 v39, 0x3e38aa3b, v65
	v_cvt_pk_bf16_f32 v113, v38, v39
	v_mul_f32_e32 v38, 0x3e38aa3b, v62
	v_mul_f32_e32 v39, 0x3e38aa3b, v63
	v_lshlrev_b32_e32 v66, 16, v58
	v_and_b32_e32 v67, 0xffff0000, v58
	v_cvt_pk_bf16_f32 v114, v38, v39
	v_mul_f32_e32 v38, 0x3e38aa3b, v68
	v_mul_f32_e32 v39, 0x3e38aa3b, v69
	v_pk_mul_f32 v[68:69], v[66:67], v[66:67]
	v_lshlrev_b32_e32 v58, 16, v59
	v_and_b32_e32 v59, 0xffff0000, v59
	v_cvt_pk_bf16_f32 v115, v38, v39
	global_store_dwordx4 v[106:107], v[112:115], off offset:2624
	v_add_f32_e32 v38, v68, v69
	v_and_b32_e32 v64, 0xffff0000, v61
	v_pk_mul_f32 v[112:113], v[58:59], v[58:59]
	v_lshlrev_b32_e32 v114, 16, v60
	v_and_b32_e32 v115, 0xffff0000, v60
	v_add_f32_e32 v38, v112, v38
	v_lshlrev_b32_e32 v65, 16, v61
	v_pk_mul_f32 v[60:61], v[114:115], v[114:115]
	v_add_f32_e32 v38, v113, v38
	v_add_f32_e32 v38, v60, v38
	v_pk_mul_f32 v[62:63], v[64:65], v[64:65]
	v_add_f32_e32 v38, v61, v38
	v_add_f32_e32 v38, v63, v38
	v_add_f32_e32 v38, v62, v38
	s_nop 1
	v_mov_b32_dpp v39, v38 quad_perm:[1,0,3,2] row_mask:0xf bank_mask:0xf
	s_waitcnt lgkmcnt(0)
	v_add_f32_e32 v38, v38, v39
	s_nop 1
	v_mov_b32_dpp v39, v38 quad_perm:[2,3,0,1] row_mask:0xf bank_mask:0xf
	s_waitcnt lgkmcnt(0)
	v_add_f32_e32 v38, v38, v39
	s_nop 1
	v_mov_b32_dpp v39, v38 row_half_mirror row_mask:0xf bank_mask:0xf
	s_waitcnt lgkmcnt(0)
	v_add_f32_e32 v38, v38, v39
	v_fmamk_f32 v38, v38, 0x3c800000, v205
	v_cmp_gt_f32_e32 vcc, s88, v38
	v_mul_f32_e32 v39, 0x4f800000, v38
	s_nop 0
	v_cndmask_b32_e32 v38, v38, v39, vcc
	v_sqrt_f32_e32 v39, v38
	s_nop 0
	v_add_u32_e32 v40, -1, v39
	v_fma_f32 v41, -v40, v39, v38
	v_cmp_ge_f32_e64 s[12:13], 0, v41
	v_add_u32_e32 v41, 1, v39
	s_nop 0
	v_cndmask_b32_e64 v40, v39, v40, s[12:13]
	v_fma_f32 v39, -v41, v39, v38
	v_cmp_lt_f32_e64 s[12:13], 0, v39
	s_nop 1
	v_cndmask_b32_e64 v39, v40, v41, s[12:13]
	v_mul_f32_e32 v40, 0x37800000, v39
	v_cndmask_b32_e32 v39, v39, v40, vcc
	v_cmp_class_f32_e32 vcc, v38, v206
	s_nop 1
	v_cndmask_b32_e32 v38, v39, v38, vcc
	v_div_scale_f32 v39, s[12:13], v38, v38, 1.0
	v_rcp_f32_e32 v40, v39
	s_nop 0
	v_fma_f32 v41, -v39, v40, 1.0
	v_fmac_f32_e32 v40, v41, v40
	v_div_scale_f32 v41, vcc, 1.0, v38, 1.0
	v_mul_f32_e32 v60, v41, v40
	v_fma_f32 v61, -v39, v60, v41
	v_fmac_f32_e32 v60, v61, v40
	v_fma_f32 v39, -v39, v60, v41
	v_div_fmas_f32 v39, v39, v40, v60
	v_div_fixup_f32 v68, v39, v38, 1.0
	v_pk_mul_f32 v[60:61], v[42:43], v[68:69] op_sel_hi:[1,0]
	s_and_b64 vcc, exec, s[10:11]
	v_pk_mul_f32 v[62:63], v[60:61], v[66:67]
	v_pk_mul_f32 v[60:61], v[44:45], v[68:69] op_sel_hi:[1,0]
	v_pk_mul_f32 v[66:67], v[48:49], v[68:69] op_sel_hi:[1,0]
	v_pk_mul_f32 v[60:61], v[60:61], v[58:59]
	v_pk_mul_f32 v[58:59], v[46:47], v[68:69] op_sel_hi:[1,0]
	v_pk_mul_f32 v[64:65], v[66:67], v[64:65] op_sel:[0,1] op_sel_hi:[1,0]
	v_pk_mul_f32 v[58:59], v[58:59], v[114:115]
	s_cbranch_vccnz .LBB0_287
	v_mov_b32_dpp v115, v65 quad_perm:[2,3,0,1] row_mask:0xf bank_mask:0xf
	v_mov_b32_dpp v66, v62 quad_perm:[2,3,0,1] row_mask:0xf bank_mask:0xf
	v_mov_b32_dpp v67, v63 quad_perm:[2,3,0,1] row_mask:0xf bank_mask:0xf
	v_mov_b32_dpp v68, v60 quad_perm:[2,3,0,1] row_mask:0xf bank_mask:0xf
	v_mov_b32_dpp v69, v61 quad_perm:[2,3,0,1] row_mask:0xf bank_mask:0xf
	v_mov_b32_dpp v112, v58 quad_perm:[2,3,0,1] row_mask:0xf bank_mask:0xf
	v_mov_b32_dpp v113, v59 quad_perm:[2,3,0,1] row_mask:0xf bank_mask:0xf
	v_mov_b32_dpp v38, v64 quad_perm:[2,3,0,1] row_mask:0xf bank_mask:0xf
	v_mov_b32_e32 v114, v65
	s_waitcnt lgkmcnt(0)
	v_pk_mul_f32 v[114:115], v[102:103], v[114:115]
	s_waitcnt lgkmcnt(0)
	v_pk_mul_f32 v[66:67], v[104:105], v[66:67]
	s_waitcnt lgkmcnt(0)
	v_pk_mul_f32 v[68:69], v[108:109], v[68:69]
	s_waitcnt lgkmcnt(0)
	v_pk_mul_f32 v[112:113], v[110:111], v[112:113]
	v_mul_f32_e32 v64, v79, v64
	s_waitcnt lgkmcnt(0)
	v_mul_f32_e32 v116, v81, v38
	v_mov_b32_e32 v65, v114
	v_mov_b32_e32 v117, v115
	v_pk_fma_f32 v[62:63], v[96:97], v[62:63], v[66:67]
	v_pk_fma_f32 v[60:61], v[98:99], v[60:61], v[68:69]
	v_pk_fma_f32 v[58:59], v[100:101], v[58:59], v[112:113]
	v_pk_add_f32 v[64:65], v[64:65], v[116:117]
; __device__ __forceinline__ unsigned pk2(float lo, float hi) { return cvtpk(lo, hi); }
; __device__ __forceinline__ float lo16(unsigned w) { return __uint_as_float(w << 16); }
; __device__ __forceinline__ float hi16(unsigned w) { return __uint_as_float(w & 0xffff0000u); }
; __device__ __forceinline__ void prep_pool_item(const KPD& kp, int l, int sc, unsigned char* lds, int tid, int lane, int wave) {
;     ...
;       for (int hd = 0; hd < 8; ++hd) {
;           const f32x4 g0 = hd < 6 ? gq0 : gk0, g1 = hd < 6 ? gq1 : gk1;
;           const float osc = hd < 6 ? 0.18033688011112042f : 1.0f;
;           const v4u v = vin[hd];
;           float x[8] = {lo16(v.x), hi16(v.x), lo16(v.y), hi16(v.y), lo16(v.z), hi16(v.z), lo16(v.w), hi16(v.w)};
;           float ss = 0.f;
; #pragma unroll
;           for (int i = 0; i < 8; ++i) ss += x[i] * x[i];
;           ss += __shfl_xor(ss, 1); ss += __shfl_xor(ss, 2); ss += __shfl_xor(ss, 4);
;           const float rstd = 1.0f / sqrtf(ss * (1.f / 64.f) + EPS);
;           x[0] *= rstd * g0.x; x[1] *= rstd * g0.y; x[2] *= rstd * g0.z; x[3] *= rstd * g0.w; x[4] *= rstd * g1.x; x[5] *= rstd * g1.y; x[6] *= rstd * g1.z; x[7] *= rstd * g1.w;
;           if (!isctx) {
; #pragma unroll
;               for (int i = 0; i < 8; ++i) { const float other = __shfl_xor(x[i], 2); x[i] = x[i] * cn[i] + other * sn[i]; } }
;           v4u o; o.x = pk2(x[0] * osc, x[1] * osc); o.y = pk2(x[2] * osc, x[3] * osc); o.z = pk2(x[4] * osc, x[5] * osc); o.w = pk2(x[6] * osc, x[7] * osc);
;           *(v4u*)(prow_ + (hd < 6 ? C_AQ + hd * 64 : C_AK + (hd - 6) * 64)) = o; } }
.LBB0_287:
	v_mul_f32_e32 v38, 0x3e38aa3b, v62
	v_mul_f32_e32 v39, 0x3e38aa3b, v63
	v_cvt_pk_bf16_f32 v66, v38, v39
	v_mul_f32_e32 v38, 0x3e38aa3b, v60
	v_mul_f32_e32 v39, 0x3e38aa3b, v61
	v_cvt_pk_bf16_f32 v67, v38, v39
	v_mul_f32_e32 v38, 0x3e38aa3b, v58
	v_mul_f32_e32 v39, 0x3e38aa3b, v59
	v_lshlrev_b32_e32 v62, 16, v54
	v_and_b32_e32 v63, 0xffff0000, v54
	v_cvt_pk_bf16_f32 v68, v38, v39
	v_mul_f32_e32 v38, 0x3e38aa3b, v64
	v_mul_f32_e32 v39, 0x3e38aa3b, v65
	v_pk_mul_f32 v[64:65], v[62:63], v[62:63]
	v_lshlrev_b32_e32 v54, 16, v55
	v_and_b32_e32 v55, 0xffff0000, v55
	v_cvt_pk_bf16_f32 v69, v38, v39
	global_store_dwordx4 v[106:107], v[66:69], off offset:2752
	v_add_f32_e32 v38, v64, v65
	v_and_b32_e32 v60, 0xffff0000, v57
	v_pk_mul_f32 v[66:67], v[54:55], v[54:55]
	v_lshlrev_b32_e32 v68, 16, v56
	v_and_b32_e32 v69, 0xffff0000, v56
	v_add_f32_e32 v38, v66, v38
	v_lshlrev_b32_e32 v61, 16, v57
	v_pk_mul_f32 v[56:57], v[68:69], v[68:69]
	v_add_f32_e32 v38, v67, v38
	v_add_f32_e32 v38, v56, v38
	v_pk_mul_f32 v[58:59], v[60:61], v[60:61]
	v_add_f32_e32 v38, v57, v38
	v_add_f32_e32 v38, v59, v38
	v_add_f32_e32 v38, v58, v38
	s_nop 1
	v_mov_b32_dpp v39, v38 quad_perm:[1,0,3,2] row_mask:0xf bank_mask:0xf
	s_waitcnt lgkmcnt(0)
	v_add_f32_e32 v38, v38, v39
	s_nop 1
	v_mov_b32_dpp v39, v38 quad_perm:[2,3,0,1] row_mask:0xf bank_mask:0xf
	s_waitcnt lgkmcnt(0)
	v_add_f32_e32 v38, v38, v39
	s_nop 1
	v_mov_b32_dpp v39, v38 row_half_mirror row_mask:0xf bank_mask:0xf
	s_waitcnt lgkmcnt(0)
	v_add_f32_e32 v38, v38, v39
	v_fmamk_f32 v38, v38, 0x3c800000, v205
	v_cmp_gt_f32_e32 vcc, s88, v38
	v_mul_f32_e32 v39, 0x4f800000, v38
	s_nop 0
	v_cndmask_b32_e32 v38, v38, v39, vcc
	v_sqrt_f32_e32 v39, v38
	s_nop 0
	v_add_u32_e32 v40, -1, v39
	v_fma_f32 v41, -v40, v39, v38
	v_cmp_ge_f32_e64 s[12:13], 0, v41
	v_add_u32_e32 v41, 1, v39
	s_nop 0
	v_cndmask_b32_e64 v40, v39, v40, s[12:13]
	v_fma_f32 v39, -v41, v39, v38
	v_cmp_lt_f32_e64 s[12:13], 0, v39
	s_nop 1
	v_cndmask_b32_e64 v39, v40, v41, s[12:13]
	v_mul_f32_e32 v40, 0x37800000, v39
	v_cndmask_b32_e32 v39, v39, v40, vcc
	v_cmp_class_f32_e32 vcc, v38, v206
	s_nop 1
	v_cndmask_b32_e32 v38, v39, v38, vcc
	v_div_scale_f32 v39, s[12:13], v38, v38, 1.0
	v_rcp_f32_e32 v40, v39
	s_nop 0
	v_fma_f32 v41, -v39, v40, 1.0
	v_fmac_f32_e32 v40, v41, v40
	v_div_scale_f32 v41, vcc, 1.0, v38, 1.0
	v_mul_f32_e32 v56, v41, v40
	v_fma_f32 v57, -v39, v56, v41
	v_fmac_f32_e32 v56, v57, v40
	v_fma_f32 v39, -v39, v56, v41
	v_div_fmas_f32 v39, v39, v40, v56
	v_div_fixup_f32 v64, v39, v38, 1.0
	v_pk_mul_f32 v[56:57], v[42:43], v[64:65] op_sel_hi:[1,0]
	s_and_b64 vcc, exec, s[10:11]
	v_pk_mul_f32 v[58:59], v[56:57], v[62:63]
	v_pk_mul_f32 v[56:57], v[44:45], v[64:65] op_sel_hi:[1,0]
	v_pk_mul_f32 v[62:63], v[48:49], v[64:65] op_sel_hi:[1,0]
	v_pk_mul_f32 v[56:57], v[56:57], v[54:55]
	v_pk_mul_f32 v[54:55], v[46:47], v[64:65] op_sel_hi:[1,0]
	v_pk_mul_f32 v[60:61], v[62:63], v[60:61] op_sel:[0,1] op_sel_hi:[1,0]
	v_pk_mul_f32 v[54:55], v[54:55], v[68:69]
	s_cbranch_vccnz .LBB0_289
	v_mov_b32_dpp v69, v61 quad_perm:[2,3,0,1] row_mask:0xf bank_mask:0xf
	v_mov_b32_dpp v62, v58 quad_perm:[2,3,0,1] row_mask:0xf bank_mask:0xf
	v_mov_b32_dpp v63, v59 quad_perm:[2,3,0,1] row_mask:0xf bank_mask:0xf
	v_mov_b32_dpp v64, v56 quad_perm:[2,3,0,1] row_mask:0xf bank_mask:0xf
	v_mov_b32_dpp v65, v57 quad_perm:[2,3,0,1] row_mask:0xf bank_mask:0xf
	v_mov_b32_dpp v66, v54 quad_perm:[2,3,0,1] row_mask:0xf bank_mask:0xf
	v_mov_b32_dpp v67, v55 quad_perm:[2,3,0,1] row_mask:0xf bank_mask:0xf
	v_mov_b32_dpp v38, v60 quad_perm:[2,3,0,1] row_mask:0xf bank_mask:0xf
	v_mov_b32_e32 v68, v61
	s_waitcnt lgkmcnt(0)
	v_pk_mul_f32 v[68:69], v[102:103], v[68:69]
	s_waitcnt lgkmcnt(0)
	v_pk_mul_f32 v[62:63], v[104:105], v[62:63]
	s_waitcnt lgkmcnt(0)
	v_pk_mul_f32 v[64:65], v[108:109], v[64:65]
	s_waitcnt lgkmcnt(0)
	v_pk_mul_f32 v[66:67], v[110:111], v[66:67]
	v_mul_f32_e32 v60, v79, v60
	s_waitcnt lgkmcnt(0)
	v_mul_f32_e32 v112, v81, v38
	v_mov_b32_e32 v61, v68
	v_mov_b32_e32 v113, v69
	v_pk_fma_f32 v[58:59], v[96:97], v[58:59], v[62:63]
	v_pk_fma_f32 v[56:57], v[98:99], v[56:57], v[64:65]
	v_pk_fma_f32 v[54:55], v[100:101], v[54:55], v[66:67]
	v_pk_add_f32 v[60:61], v[60:61], v[112:113]
.LBB0_289:
	v_mul_f32_e32 v38, 0x3e38aa3b, v58
	v_mul_f32_e32 v39, 0x3e38aa3b, v59
	v_cvt_pk_bf16_f32 v62, v38, v39
	v_mul_f32_e32 v38, 0x3e38aa3b, v56
	v_mul_f32_e32 v39, 0x3e38aa3b, v57
	v_cvt_pk_bf16_f32 v63, v38, v39
	v_mul_f32_e32 v38, 0x3e38aa3b, v54
	v_mul_f32_e32 v39, 0x3e38aa3b, v55
	v_lshlrev_b32_e32 v58, 16, v50
	v_and_b32_e32 v59, 0xffff0000, v50
	v_cvt_pk_bf16_f32 v64, v38, v39
	v_mul_f32_e32 v38, 0x3e38aa3b, v60
	v_mul_f32_e32 v39, 0x3e38aa3b, v61
	v_cvt_pk_bf16_f32 v65, v38, v39
	global_store_dwordx4 v[106:107], v[62:65], off offset:2880
	v_pk_mul_f32 v[60:61], v[58:59], v[58:59]
	v_and_b32_e32 v54, 0xffff0000, v53
	v_lshlrev_b32_e32 v62, 16, v51
	v_and_b32_e32 v63, 0xffff0000, v51
	v_pk_mul_f32 v[50:51], v[62:63], v[62:63]
	v_add_f32_e32 v38, v60, v61
	v_lshlrev_b32_e32 v64, 16, v52
	v_and_b32_e32 v65, 0xffff0000, v52
	v_add_f32_e32 v38, v50, v38
	v_lshlrev_b32_e32 v55, 16, v53
	v_pk_mul_f32 v[52:53], v[64:65], v[64:65]
	v_add_f32_e32 v38, v51, v38
	v_add_f32_e32 v38, v52, v38
	v_pk_mul_f32 v[56:57], v[54:55], v[54:55]
	v_add_f32_e32 v38, v53, v38
	v_add_f32_e32 v38, v57, v38
	v_add_f32_e32 v38, v56, v38
	s_nop 1
	v_mov_b32_dpp v39, v38 quad_perm:[1,0,3,2] row_mask:0xf bank_mask:0xf
	s_waitcnt lgkmcnt(0)
	v_add_f32_e32 v38, v38, v39
	s_nop 1
	v_mov_b32_dpp v39, v38 quad_perm:[2,3,0,1] row_mask:0xf bank_mask:0xf
	s_waitcnt lgkmcnt(0)
; __device__ __forceinline__ unsigned pk2(float lo, float hi) { return cvtpk(lo, hi); }
; __device__ __forceinline__ float lo16(unsigned w) { return __uint_as_float(w << 16); }
; __device__ __forceinline__ float hi16(unsigned w) { return __uint_as_float(w & 0xffff0000u); }
; __device__ __forceinline__ void prep_pool_item(const KPD& kp, int l, int sc, unsigned char* lds, int tid, int lane, int wave) {
;     ...
;       for (int hd = 0; hd < 8; ++hd) {
;           const f32x4 g0 = hd < 6 ? gq0 : gk0, g1 = hd < 6 ? gq1 : gk1;
;           const float osc = hd < 6 ? 0.18033688011112042f : 1.0f;
;           const v4u v = vin[hd];
;           float x[8] = {lo16(v.x), hi16(v.x), lo16(v.y), hi16(v.y), lo16(v.z), hi16(v.z), lo16(v.w), hi16(v.w)};
;           float ss = 0.f;
; #pragma unroll
;           for (int i = 0; i < 8; ++i) ss += x[i] * x[i];
;           ss += __shfl_xor(ss, 1); ss += __shfl_xor(ss, 2); ss += __shfl_xor(ss, 4);
;           const float rstd = 1.0f / sqrtf(ss * (1.f / 64.f) + EPS);
;           x[0] *= rstd * g0.x; x[1] *= rstd * g0.y; x[2] *= rstd * g0.z; x[3] *= rstd * g0.w; x[4] *= rstd * g1.x; x[5] *= rstd * g1.y; x[6] *= rstd * g1.z; x[7] *= rstd * g1.w;
;           if (!isctx) {
; #pragma unroll
;               for (int i = 0; i < 8; ++i) { const float other = __shfl_xor(x[i], 2); x[i] = x[i] * cn[i] + other * sn[i]; } }
;           v4u o; o.x = pk2(x[0] * osc, x[1] * osc); o.y = pk2(x[2] * osc, x[3] * osc); o.z = pk2(x[4] * osc, x[5] * osc); o.w = pk2(x[6] * osc, x[7] * osc);
;           *(v4u*)(prow_ + (hd < 6 ? C_AQ + hd * 64 : C_AK + (hd - 6) * 64)) = o; } }
	v_add_f32_e32 v38, v38, v39
	s_nop 1
	v_mov_b32_dpp v39, v38 row_half_mirror row_mask:0xf bank_mask:0xf
	s_waitcnt lgkmcnt(0)
	v_add_f32_e32 v38, v38, v39
	v_fmamk_f32 v38, v38, 0x3c800000, v205
	v_cmp_gt_f32_e32 vcc, s88, v38
	v_mul_f32_e32 v39, 0x4f800000, v38
	s_nop 0
	v_cndmask_b32_e32 v38, v38, v39, vcc
	v_sqrt_f32_e32 v39, v38
	s_nop 0
	v_add_u32_e32 v40, -1, v39
	v_fma_f32 v41, -v40, v39, v38
	v_cmp_ge_f32_e64 s[12:13], 0, v41
	v_add_u32_e32 v41, 1, v39
	s_nop 0
	v_cndmask_b32_e64 v40, v39, v40, s[12:13]
	v_fma_f32 v39, -v41, v39, v38
	v_cmp_lt_f32_e64 s[12:13], 0, v39
	s_nop 1
	v_cndmask_b32_e64 v39, v40, v41, s[12:13]
	v_mul_f32_e32 v40, 0x37800000, v39
	v_cndmask_b32_e32 v39, v39, v40, vcc
	v_cmp_class_f32_e32 vcc, v38, v206
	s_nop 1
	v_cndmask_b32_e32 v38, v39, v38, vcc
	v_div_scale_f32 v39, s[12:13], v38, v38, 1.0
	v_rcp_f32_e32 v40, v39
	s_nop 0
	v_fma_f32 v41, -v39, v40, 1.0
	v_fmac_f32_e32 v40, v41, v40
	v_div_scale_f32 v41, vcc, 1.0, v38, 1.0
	v_mul_f32_e32 v50, v41, v40
	v_fma_f32 v51, -v39, v50, v41
	v_fmac_f32_e32 v50, v51, v40
	v_fma_f32 v39, -v39, v50, v41
	v_div_fmas_f32 v39, v39, v40, v50
	v_div_fixup_f32 v52, v39, v38, 1.0
	v_pk_mul_f32 v[42:43], v[42:43], v[52:53] op_sel_hi:[1,0]
	s_and_b64 vcc, exec, s[10:11]
	v_pk_mul_f32 v[50:51], v[42:43], v[58:59]
	v_pk_mul_f32 v[42:43], v[44:45], v[52:53] op_sel_hi:[1,0]
	s_nop 0
	v_pk_mul_f32 v[44:45], v[42:43], v[62:63]
	v_pk_mul_f32 v[42:43], v[46:47], v[52:53] op_sel_hi:[1,0]
	v_pk_mul_f32 v[46:47], v[48:49], v[52:53] op_sel_hi:[1,0]
	v_pk_mul_f32 v[42:43], v[42:43], v[64:65]
	v_pk_mul_f32 v[46:47], v[46:47], v[54:55] op_sel:[0,1] op_sel_hi:[1,0]
	s_cbranch_vccnz .LBB0_291
	s_nop 0
	v_mov_b32_dpp v57, v47 quad_perm:[2,3,0,1] row_mask:0xf bank_mask:0xf
	v_mov_b32_dpp v48, v50 quad_perm:[2,3,0,1] row_mask:0xf bank_mask:0xf
	v_mov_b32_dpp v49, v51 quad_perm:[2,3,0,1] row_mask:0xf bank_mask:0xf
	v_mov_b32_dpp v52, v44 quad_perm:[2,3,0,1] row_mask:0xf bank_mask:0xf
	v_mov_b32_dpp v53, v45 quad_perm:[2,3,0,1] row_mask:0xf bank_mask:0xf
	v_mov_b32_dpp v54, v42 quad_perm:[2,3,0,1] row_mask:0xf bank_mask:0xf
	v_mov_b32_dpp v55, v43 quad_perm:[2,3,0,1] row_mask:0xf bank_mask:0xf
	v_mov_b32_dpp v38, v46 quad_perm:[2,3,0,1] row_mask:0xf bank_mask:0xf
	v_mov_b32_e32 v56, v47
	s_waitcnt lgkmcnt(0)
	v_pk_mul_f32 v[56:57], v[102:103], v[56:57]
	s_waitcnt lgkmcnt(0)
	v_pk_mul_f32 v[48:49], v[104:105], v[48:49]
	s_waitcnt lgkmcnt(0)
	v_pk_mul_f32 v[52:53], v[108:109], v[52:53]
	s_waitcnt lgkmcnt(0)
	v_pk_mul_f32 v[54:55], v[110:111], v[54:55]
	v_mul_f32_e32 v46, v79, v46
	s_waitcnt lgkmcnt(0)
	v_mul_f32_e32 v58, v81, v38
	v_mov_b32_e32 v47, v56
	v_mov_b32_e32 v59, v57
	v_pk_fma_f32 v[50:51], v[96:97], v[50:51], v[48:49]
	v_pk_fma_f32 v[44:45], v[98:99], v[44:45], v[52:53]
	v_pk_fma_f32 v[42:43], v[100:101], v[42:43], v[54:55]
	v_pk_add_f32 v[46:47], v[46:47], v[58:59]
.LBB0_291:
	v_mul_f32_e32 v38, 0x3e38aa3b, v50
	v_mul_f32_e32 v39, 0x3e38aa3b, v51
	v_cvt_pk_bf16_f32 v48, v38, v39
	v_mul_f32_e32 v38, 0x3e38aa3b, v44
	v_mul_f32_e32 v39, 0x3e38aa3b, v45
	v_cvt_pk_bf16_f32 v49, v38, v39
	v_mul_f32_e32 v38, 0x3e38aa3b, v42
	v_mul_f32_e32 v39, 0x3e38aa3b, v43
	v_cvt_pk_bf16_f32 v50, v38, v39
	v_mul_f32_e32 v38, 0x3e38aa3b, v46
	v_mul_f32_e32 v39, 0x3e38aa3b, v47
	v_cvt_pk_bf16_f32 v51, v38, v39
	v_lshlrev_b32_e32 v46, 16, v14
	v_and_b32_e32 v47, 0xffff0000, v14
	global_store_dwordx4 v[106:107], v[48:51], off offset:3008
	v_lshlrev_b32_e32 v52, 16, v16
	v_and_b32_e32 v53, 0xffff0000, v16
	v_pk_mul_f32 v[48:49], v[46:47], v[46:47]
	v_lshlrev_b32_e32 v50, 16, v15
	v_and_b32_e32 v51, 0xffff0000, v15
	v_pk_mul_f32 v[14:15], v[50:51], v[50:51]
	v_add_f32_e32 v38, v48, v49
	v_add_f32_e32 v14, v14, v38
	v_and_b32_e32 v44, 0xffff0000, v17
	v_lshlrev_b32_e32 v45, 16, v17
	v_pk_mul_f32 v[16:17], v[52:53], v[52:53]
	v_add_f32_e32 v14, v15, v14
	v_add_f32_e32 v14, v16, v14
	v_pk_mul_f32 v[42:43], v[44:45], v[44:45]
	v_add_f32_e32 v14, v17, v14
	v_add_f32_e32 v14, v43, v14
	v_add_f32_e32 v14, v42, v14
	s_nop 1
	v_mov_b32_dpp v15, v14 quad_perm:[1,0,3,2] row_mask:0xf bank_mask:0xf
	s_waitcnt lgkmcnt(0)
	v_add_f32_e32 v14, v14, v15
	s_nop 1
	v_mov_b32_dpp v15, v14 quad_perm:[2,3,0,1] row_mask:0xf bank_mask:0xf
	s_waitcnt lgkmcnt(0)
	v_add_f32_e32 v14, v14, v15
	s_nop 1
	v_mov_b32_dpp v15, v14 row_half_mirror row_mask:0xf bank_mask:0xf
	s_waitcnt lgkmcnt(0)
	v_add_f32_e32 v14, v14, v15
	v_fmamk_f32 v14, v14, 0x3c800000, v205
	v_cmp_gt_f32_e32 vcc, s88, v14
	v_mul_f32_e32 v15, 0x4f800000, v14
	s_nop 0
	v_cndmask_b32_e32 v14, v14, v15, vcc
	v_sqrt_f32_e32 v15, v14
	s_nop 0
	v_add_u32_e32 v16, -1, v15
	v_fma_f32 v17, -v16, v15, v14
	v_cmp_ge_f32_e64 s[12:13], 0, v17
	v_add_u32_e32 v17, 1, v15
	s_nop 0
	v_cndmask_b32_e64 v16, v15, v16, s[12:13]
	v_fma_f32 v15, -v17, v15, v14
	v_cmp_lt_f32_e64 s[12:13], 0, v15
	s_nop 1
	v_cndmask_b32_e64 v15, v16, v17, s[12:13]
	v_mul_f32_e32 v16, 0x37800000, v15
	v_cndmask_b32_e32 v15, v15, v16, vcc
	v_cmp_class_f32_e32 vcc, v14, v206
	s_nop 1
	v_cndmask_b32_e32 v14, v15, v14, vcc
	v_div_scale_f32 v15, s[12:13], v14, v14, 1.0
	v_rcp_f32_e32 v16, v15
	s_nop 0
	v_fma_f32 v17, -v15, v16, 1.0
	v_fmac_f32_e32 v16, v17, v16
	v_div_scale_f32 v17, vcc, 1.0, v14, 1.0
	v_mul_f32_e32 v38, v17, v16
	v_fma_f32 v39, -v15, v38, v17
	v_fmac_f32_e32 v38, v39, v16
	v_fma_f32 v15, -v15, v38, v17
	v_div_fmas_f32 v15, v15, v16, v38
	v_div_fixup_f32 v48, v15, v14, 1.0
	s_waitcnt vmcnt(7)
	v_pk_mul_f32 v[14:15], v[2:3], v[48:49] op_sel_hi:[1,0]
	v_pk_mul_f32 v[16:17], v[4:5], v[48:49] op_sel_hi:[1,0]
	v_pk_mul_f32 v[14:15], v[14:15], v[46:47]
	s_waitcnt vmcnt(6)
	v_pk_mul_f32 v[42:43], v[6:7], v[48:49] op_sel_hi:[1,0]
	v_pk_mul_f32 v[46:47], v[8:9], v[48:49] op_sel_hi:[1,0]
	v_pk_mul_f32 v[16:17], v[16:17], v[50:51]
	v_pk_mul_f32 v[42:43], v[42:43], v[52:53]
	v_pk_mul_f32 v[44:45], v[46:47], v[44:45] op_sel:[0,1] op_sel_hi:[1,0]
	s_and_b64 vcc, exec, s[10:11]
	s_cbranch_vccnz .LBB0_293
; __device__ __forceinline__ unsigned pk2(float lo, float hi) { return cvtpk(lo, hi); }
; __device__ __forceinline__ float lo16(unsigned w) { return __uint_as_float(w << 16); }
; __device__ __forceinline__ float hi16(unsigned w) { return __uint_as_float(w & 0xffff0000u); }
; __device__ __forceinline__ void prep_pool_item(const KPD& kp, int l, int sc, unsigned char* lds, int tid, int lane, int wave) {
;     ...
;       for (int hd = 0; hd < 8; ++hd) {
;           const f32x4 g0 = hd < 6 ? gq0 : gk0, g1 = hd < 6 ? gq1 : gk1;
;           const float osc = hd < 6 ? 0.18033688011112042f : 1.0f;
;           const v4u v = vin[hd];
;           float x[8] = {lo16(v.x), hi16(v.x), lo16(v.y), hi16(v.y), lo16(v.z), hi16(v.z), lo16(v.w), hi16(v.w)};
;           float ss = 0.f;
; #pragma unroll
;           for (int i = 0; i < 8; ++i) ss += x[i] * x[i];
;           ss += __shfl_xor(ss, 1); ss += __shfl_xor(ss, 2); ss += __shfl_xor(ss, 4);
;           const float rstd = 1.0f / sqrtf(ss * (1.f / 64.f) + EPS);
;           x[0] *= rstd * g0.x; x[1] *= rstd * g0.y; x[2] *= rstd * g0.z; x[3] *= rstd * g0.w; x[4] *= rstd * g1.x; x[5] *= rstd * g1.y; x[6] *= rstd * g1.z; x[7] *= rstd * g1.w;
;           if (!isctx) {
; #pragma unroll
;               for (int i = 0; i < 8; ++i) { const float other = __shfl_xor(x[i], 2); x[i] = x[i] * cn[i] + other * sn[i]; } }
;           v4u o; o.x = pk2(x[0] * osc, x[1] * osc); o.y = pk2(x[2] * osc, x[3] * osc); o.z = pk2(x[4] * osc, x[5] * osc); o.w = pk2(x[6] * osc, x[7] * osc);
;           *(v4u*)(prow_ + (hd < 6 ? C_AQ + hd * 64 : C_AK + (hd - 6) * 64)) = o; } }
	v_mov_b32_dpp v53, v45 quad_perm:[2,3,0,1] row_mask:0xf bank_mask:0xf
	v_mov_b32_dpp v46, v14 quad_perm:[2,3,0,1] row_mask:0xf bank_mask:0xf
	v_mov_b32_dpp v47, v15 quad_perm:[2,3,0,1] row_mask:0xf bank_mask:0xf
	v_mov_b32_dpp v48, v16 quad_perm:[2,3,0,1] row_mask:0xf bank_mask:0xf
	v_mov_b32_dpp v49, v17 quad_perm:[2,3,0,1] row_mask:0xf bank_mask:0xf
	v_mov_b32_dpp v50, v42 quad_perm:[2,3,0,1] row_mask:0xf bank_mask:0xf
	v_mov_b32_dpp v51, v43 quad_perm:[2,3,0,1] row_mask:0xf bank_mask:0xf
	v_mov_b32_dpp v38, v44 quad_perm:[2,3,0,1] row_mask:0xf bank_mask:0xf
	v_mov_b32_e32 v52, v45
	s_waitcnt lgkmcnt(0)
	v_pk_mul_f32 v[52:53], v[102:103], v[52:53]
	s_waitcnt lgkmcnt(0)
	v_pk_mul_f32 v[46:47], v[104:105], v[46:47]
	s_waitcnt lgkmcnt(0)
	v_pk_mul_f32 v[48:49], v[108:109], v[48:49]
	s_waitcnt lgkmcnt(0)
	v_pk_mul_f32 v[50:51], v[110:111], v[50:51]
	v_mul_f32_e32 v44, v79, v44
	s_waitcnt lgkmcnt(0)
	v_mul_f32_e32 v54, v81, v38
	v_mov_b32_e32 v45, v52
	v_mov_b32_e32 v55, v53
	v_pk_fma_f32 v[14:15], v[96:97], v[14:15], v[46:47]
	v_pk_fma_f32 v[16:17], v[98:99], v[16:17], v[48:49]
	v_pk_fma_f32 v[42:43], v[100:101], v[42:43], v[50:51]
	v_pk_add_f32 v[44:45], v[44:45], v[54:55]
.LBB0_293:
	v_cvt_pk_bf16_f32 v14, v14, v15
	v_cvt_pk_bf16_f32 v15, v16, v17
	v_cvt_pk_bf16_f32 v16, v42, v43
	v_lshlrev_b32_e32 v42, 16, v10
	v_and_b32_e32 v43, 0xffff0000, v10
	v_cvt_pk_bf16_f32 v17, v44, v45
	v_pk_mul_f32 v[44:45], v[42:43], v[42:43]
	v_lshlrev_b32_e32 v10, 16, v11
	v_and_b32_e32 v11, 0xffff0000, v11
	v_pk_mul_f32 v[46:47], v[10:11], v[10:11]
	v_add_f32_e32 v38, v44, v45
	v_lshlrev_b32_e32 v48, 16, v12
	v_and_b32_e32 v49, 0xffff0000, v12
	v_add_f32_e32 v38, v46, v38
	global_store_dwordx4 v[106:107], v[14:17], off offset:3136
	v_add_f32_e32 v38, v47, v38
	s_nop 0
	v_and_b32_e32 v14, 0xffff0000, v13
	v_lshlrev_b32_e32 v15, 16, v13
	v_pk_mul_f32 v[12:13], v[48:49], v[48:49]
	v_pk_mul_f32 v[16:17], v[14:15], v[14:15]
	v_add_f32_e32 v12, v12, v38
	v_add_f32_e32 v12, v13, v12
	v_add_f32_e32 v12, v17, v12
	v_add_f32_e32 v12, v16, v12
	s_nop 1
	v_mov_b32_dpp v13, v12 quad_perm:[1,0,3,2] row_mask:0xf bank_mask:0xf
	s_waitcnt lgkmcnt(0)
	v_add_f32_e32 v12, v12, v13
	s_nop 1
	v_mov_b32_dpp v13, v12 quad_perm:[2,3,0,1] row_mask:0xf bank_mask:0xf
	s_waitcnt lgkmcnt(0)
	v_add_f32_e32 v12, v12, v13
	s_nop 1
	v_mov_b32_dpp v13, v12 row_half_mirror row_mask:0xf bank_mask:0xf
	s_waitcnt lgkmcnt(0)
	v_add_f32_e32 v12, v12, v13
	v_fmamk_f32 v12, v12, 0x3c800000, v205
	v_cmp_gt_f32_e32 vcc, s88, v12
	v_mul_f32_e32 v13, 0x4f800000, v12
	s_nop 0
	v_cndmask_b32_e32 v12, v12, v13, vcc
	v_sqrt_f32_e32 v13, v12
	s_nop 0
	v_add_u32_e32 v16, -1, v13
	v_fma_f32 v17, -v16, v13, v12
	v_cmp_ge_f32_e64 s[12:13], 0, v17
	v_add_u32_e32 v17, 1, v13
	s_nop 0
	v_cndmask_b32_e64 v16, v13, v16, s[12:13]
	v_fma_f32 v13, -v17, v13, v12
	v_cmp_lt_f32_e64 s[12:13], 0, v13
	s_nop 1
	v_cndmask_b32_e64 v13, v16, v17, s[12:13]
	v_mul_f32_e32 v16, 0x37800000, v13
	v_cndmask_b32_e32 v13, v13, v16, vcc
	v_cmp_class_f32_e32 vcc, v12, v206
	s_nop 1
	v_cndmask_b32_e32 v12, v13, v12, vcc
	v_div_scale_f32 v13, s[12:13], v12, v12, 1.0
	v_rcp_f32_e32 v16, v13
	s_nop 0
	v_fma_f32 v17, -v13, v16, 1.0
	v_fmac_f32_e32 v16, v17, v16
	v_div_scale_f32 v17, vcc, 1.0, v12, 1.0
	v_mul_f32_e32 v38, v17, v16
	v_fma_f32 v39, -v13, v38, v17
	v_fmac_f32_e32 v38, v39, v16
	v_fma_f32 v13, -v13, v38, v17
	v_div_fmas_f32 v13, v13, v16, v38
	v_div_fixup_f32 v12, v13, v12, 1.0
	v_pk_mul_f32 v[2:3], v[2:3], v[12:13] op_sel_hi:[1,0]
	v_pk_mul_f32 v[4:5], v[4:5], v[12:13] op_sel_hi:[1,0]
	v_pk_mul_f32 v[6:7], v[6:7], v[12:13] op_sel_hi:[1,0]
	v_pk_mul_f32 v[8:9], v[8:9], v[12:13] op_sel_hi:[1,0]
	v_pk_mul_f32 v[2:3], v[2:3], v[42:43]
	v_pk_mul_f32 v[4:5], v[4:5], v[10:11]
	v_pk_mul_f32 v[6:7], v[6:7], v[48:49]
	v_pk_mul_f32 v[8:9], v[8:9], v[14:15] op_sel:[0,1] op_sel_hi:[1,0]
	s_and_b64 vcc, exec, s[10:11]
	s_cbranch_vccnz .LBB0_295
	v_mov_b32_dpp v43, v9 quad_perm:[2,3,0,1] row_mask:0xf bank_mask:0xf
	v_mov_b32_dpp v10, v2 quad_perm:[2,3,0,1] row_mask:0xf bank_mask:0xf
	v_mov_b32_dpp v11, v3 quad_perm:[2,3,0,1] row_mask:0xf bank_mask:0xf
	v_mov_b32_dpp v12, v4 quad_perm:[2,3,0,1] row_mask:0xf bank_mask:0xf
	v_mov_b32_dpp v13, v5 quad_perm:[2,3,0,1] row_mask:0xf bank_mask:0xf
	v_mov_b32_dpp v14, v6 quad_perm:[2,3,0,1] row_mask:0xf bank_mask:0xf
	v_mov_b32_dpp v15, v7 quad_perm:[2,3,0,1] row_mask:0xf bank_mask:0xf
	v_mov_b32_dpp v16, v8 quad_perm:[2,3,0,1] row_mask:0xf bank_mask:0xf
	v_mov_b32_e32 v42, v9
	s_waitcnt lgkmcnt(0)
	v_pk_mul_f32 v[42:43], v[102:103], v[42:43]
	s_waitcnt lgkmcnt(0)
	v_pk_mul_f32 v[10:11], v[104:105], v[10:11]
	s_waitcnt lgkmcnt(0)
	v_pk_mul_f32 v[12:13], v[108:109], v[12:13]
	s_waitcnt lgkmcnt(0)
	v_pk_mul_f32 v[14:15], v[110:111], v[14:15]
	v_mul_f32_e32 v8, v79, v8
	s_waitcnt lgkmcnt(0)
	v_mul_f32_e32 v16, v81, v16
	v_mov_b32_e32 v9, v42
	v_mov_b32_e32 v17, v43
	v_pk_fma_f32 v[2:3], v[96:97], v[2:3], v[10:11]
	v_pk_fma_f32 v[4:5], v[98:99], v[4:5], v[12:13]
	v_pk_fma_f32 v[6:7], v[100:101], v[6:7], v[14:15]
	v_pk_add_f32 v[8:9], v[8:9], v[16:17]
